# speedup vs baseline: 1.0014x; 1.0014x over previous
.LBB0_158:
	v_mul_f32_e32 v112, v68, v112
	v_sub_f32_e32 v112, v111, v112
	v_cndmask_b32_e64 v112, v112, v153, s[4:5]
	v_sub_f32_e32 v113, v164, v112
	v_exp_f32_e32 v113, v113
	v_sub_f32_e32 v115, v163, v112
	v_exp_f32_e32 v115, v115
	v_sub_f32_e32 v116, v162, v112
	v_exp_f32_e32 v117, v116
	v_sub_f32_e32 v116, v161, v112
	v_exp_f32_e32 v118, v116
	v_sub_f32_e32 v116, v160, v112
	v_add_f32_e32 v234, 0, v113
	v_exp_f32_e32 v119, v116
	v_sub_f32_e32 v116, v159, v112
	v_add_f32_e32 v234, v115, v234
	v_exp_f32_e32 v120, v116
	v_sub_f32_e32 v116, v158, v112
	v_add_f32_e32 v234, v117, v234
	v_exp_f32_e32 v121, v116
	v_sub_f32_e32 v116, v157, v112
	v_add_f32_e32 v234, v118, v234
	v_exp_f32_e32 v122, v116
	v_mov_b32_e32 v235, v112
	v_add_f32_e32 v234, v119, v234
	v_add_f32_e32 v234, v120, v234
	v_add_f32_e32 v234, v121, v234
	v_add_f32_e32 v234, v122, v234
	v_cvt_pk_bf16_f32 v112, v113, v115
	v_cvt_pk_bf16_f32 v113, v117, v118
	v_cvt_pk_bf16_f32 v114, v119, v120
	v_cvt_pk_bf16_f32 v115, v121, v122
	s_waitcnt lgkmcnt(0)
	s_nop 1
	v_mfma_f32_16x16x32_bf16 v[56:59], v[170:173], v[112:115], v[56:59]
	v_sub_f32_e32 v116, v147, v235
	v_exp_f32_e32 v116, v116
	v_sub_f32_e32 v123, v146, v235
	v_exp_f32_e32 v123, v123
	v_mfma_f32_16x16x32_bf16 v[60:63], v[178:181], v[112:115], v[60:63]
	v_sub_f32_e32 v124, v145, v235
	v_exp_f32_e32 v124, v124
	v_sub_f32_e32 v125, v144, v235
	v_exp_f32_e32 v125, v125
	v_mfma_f32_16x16x32_bf16 v[52:55], v[186:189], v[112:115], v[52:55]
	v_sub_f32_e32 v139, v143, v235
	v_exp_f32_e32 v139, v139
	v_sub_f32_e32 v142, v142, v235
	v_exp_f32_e32 v142, v142
	v_mfma_f32_16x16x32_bf16 v[48:51], v[194:197], v[112:115], v[48:51]
	v_sub_f32_e32 v141, v141, v235
	v_exp_f32_e32 v141, v141
	v_sub_f32_e32 v236, v140, v235
	v_exp_f32_e32 v140, v236
	v_mfma_f32_16x16x32_bf16 v[44:47], v[202:205], v[112:115], v[44:47]
	v_add_f32_e32 v234, v116, v234
	v_add_f32_e32 v234, v123, v234
	v_add_f32_e32 v234, v124, v234
	v_add_f32_e32 v234, v125, v234
	v_mfma_f32_16x16x32_bf16 v[40:43], v[210:213], v[112:115], v[40:43]
	v_add_f32_e32 v234, v139, v234
	v_add_f32_e32 v234, v142, v234
	v_add_f32_e32 v234, v141, v234
	v_add_f32_e32 v144, v140, v234
	v_mfma_f32_16x16x32_bf16 v[36:39], v[218:221], v[112:115], v[36:39]
	v_cvt_pk_bf16_f32 v116, v116, v123
	v_cvt_pk_bf16_f32 v118, v139, v142
	v_cvt_pk_bf16_f32 v119, v141, v140
	v_cvt_pk_bf16_f32 v117, v124, v125
	v_mfma_f32_16x16x32_bf16 v[32:35], v[226:229], v[112:115], v[32:35]
	v_fmac_f32_e32 v144, v137, v110
	v_mov_b32_e32 v137, v144
	v_mfma_f32_16x16x32_bf16 v[56:59], v[174:177], v[116:119], v[56:59]
	v_mfma_f32_16x16x32_bf16 v[60:63], v[182:185], v[116:119], v[60:63]
	v_mfma_f32_16x16x32_bf16 v[52:55], v[190:193], v[116:119], v[52:55]
	v_mfma_f32_16x16x32_bf16 v[48:51], v[198:201], v[116:119], v[48:51]
	v_mfma_f32_16x16x32_bf16 v[44:47], v[206:209], v[116:119], v[44:47]
	v_mfma_f32_16x16x32_bf16 v[40:43], v[214:217], v[116:119], v[40:43]
	v_mfma_f32_16x16x32_bf16 v[36:39], v[222:225], v[116:119], v[36:39]
	v_mfma_f32_16x16x32_bf16 v[32:35], v[230:233], v[116:119], v[32:35]
	v_mov_b32_e32 v139, v111
	s_or_b64 exec, exec, s[42:43]
	s_andn2_b64 vcc, exec, s[40:41]
	s_cbranch_vccnz .LBB0_137
